# GEMM K-loop back edge rotated (7.11): next-iteration scalar setup before the loop-back barrier, direct jump to the first ds_read for plain-epilogue GEMMs
# baseline (speedup 1.0000x reference)
.Lkl_fast:
	v_add_u32_e32 v144, s47, v193
	ds_read_b128 v[132:135], v144
	ds_read_b128 v[136:139], v144 offset:1024
	ds_read_b128 v[140:143], v144 offset:2048
	ds_read_b128 v[144:147], v144 offset:3072
	s_cmp_eq_u32 s71, s46
	s_cselect_b32 s9, s13, s9
	s_cselect_b32 s8, s12, s8
	s_cselect_b32 s31, s57, s31
	s_cselect_b32 s30, s56, s30
	v_lshl_add_u64 v[190:191], v[128:129], 0, s[4:5]
	s_add_i32 m0, s19, 0xc000
	ds_read_b128 v[148:151], v202
	ds_read_b128 v[152:155], v202 offset:1024
	ds_read_b128 v[156:159], v202 offset:2048
	ds_read_b128 v[160:163], v202 offset:3072
	ds_read_b128 v[164:167], v202 offset:4096
	ds_read_b128 v[204:207], v202 offset:5120
	ds_read_b128 v[208:211], v202 offset:6144
	ds_read_b128 v[212:215], v202 offset:7168
	global_load_lds_dwordx4 v[190:191], off
	v_lshl_add_u64 v[190:191], v[130:131], 0, s[4:5]
	s_add_i32 m0, s19, 0xe000
	s_nop 0
	global_load_lds_dwordx4 v[190:191], off
	s_waitcnt lgkmcnt(8)
	s_barrier
	s_waitcnt lgkmcnt(0)
	s_setprio 1
	s_waitcnt lgkmcnt(0)
	v_mfma_f32_16x16x32_bf16 v[124:127], v[132:135], v[148:151], v[124:127]
	v_mfma_f32_16x16x32_bf16 v[120:123], v[140:143], v[148:151], v[120:123]
	v_mfma_f32_16x16x32_bf16 v[108:111], v[132:135], v[156:159], v[108:111]
	v_mfma_f32_16x16x32_bf16 v[104:107], v[140:143], v[156:159], v[104:107]
	v_mfma_f32_16x16x32_bf16 v[92:95], v[132:135], v[164:167], v[92:95]
	v_mfma_f32_16x16x32_bf16 v[88:91], v[140:143], v[164:167], v[88:91]
	v_mfma_f32_16x16x32_bf16 v[76:79], v[132:135], v[208:211], v[76:79]
	v_mfma_f32_16x16x32_bf16 v[72:75], v[140:143], v[208:211], v[72:75]
	v_mfma_f32_16x16x32_bf16 v[124:127], v[136:139], v[152:155], v[124:127]
	v_mfma_f32_16x16x32_bf16 v[120:123], v[144:147], v[152:155], v[120:123]
	v_mfma_f32_16x16x32_bf16 v[108:111], v[136:139], v[160:163], v[108:111]
	v_mfma_f32_16x16x32_bf16 v[104:107], v[144:147], v[160:163], v[104:107]
	v_mfma_f32_16x16x32_bf16 v[92:95], v[136:139], v[204:207], v[92:95]
	v_mfma_f32_16x16x32_bf16 v[88:91], v[144:147], v[204:207], v[88:91]
	v_mfma_f32_16x16x32_bf16 v[76:79], v[136:139], v[212:215], v[76:79]
	v_mfma_f32_16x16x32_bf16 v[72:75], v[144:147], v[212:215], v[72:75]
	s_setprio 0
	s_barrier
	s_add_i32 s46, 0, 0x14000
	v_add_u32_e32 v190, s46, v193
	s_add_i32 s47, s47, s53
	ds_read_b128 v[216:219], v190
	ds_read_b128 v[220:223], v190 offset:1024
	ds_read_b128 v[232:235], v190 offset:2048
	ds_read_b128 v[240:243], v190 offset:3072
	v_lshl_add_u64 v[190:191], s[30:31], 0, v[180:181]
	s_mov_b32 m0, s47
	v_lshl_add_u64 v[224:225], s[30:31], 0, v[176:177]
	global_load_lds_dwordx4 v[190:191], off
	s_add_i32 m0, s47, 0x2000
	s_nop 0
	global_load_lds_dwordx4 v[224:225], off
	s_barrier
	s_waitcnt lgkmcnt(0)
	s_setprio 1
	s_waitcnt lgkmcnt(0)
	v_mfma_f32_16x16x32_bf16 v[116:119], v[216:219], v[148:151], v[116:119]
	v_mfma_f32_16x16x32_bf16 v[112:115], v[232:235], v[148:151], v[112:115]
	v_mfma_f32_16x16x32_bf16 v[100:103], v[216:219], v[156:159], v[100:103]
	v_mfma_f32_16x16x32_bf16 v[96:99], v[232:235], v[156:159], v[96:99]
	v_mfma_f32_16x16x32_bf16 v[84:87], v[216:219], v[164:167], v[84:87]
	v_mfma_f32_16x16x32_bf16 v[80:83], v[232:235], v[164:167], v[80:83]
	v_mfma_f32_16x16x32_bf16 v[68:71], v[216:219], v[208:211], v[68:71]
	v_mfma_f32_16x16x32_bf16 v[64:67], v[232:235], v[208:211], v[64:67]
	v_mfma_f32_16x16x32_bf16 v[116:119], v[220:223], v[152:155], v[116:119]
	v_mfma_f32_16x16x32_bf16 v[112:115], v[240:243], v[152:155], v[112:115]
	v_mfma_f32_16x16x32_bf16 v[100:103], v[220:223], v[160:163], v[100:103]
	v_mfma_f32_16x16x32_bf16 v[96:99], v[240:243], v[160:163], v[96:99]
	v_mfma_f32_16x16x32_bf16 v[84:87], v[220:223], v[204:207], v[84:87]
	v_mfma_f32_16x16x32_bf16 v[80:83], v[240:243], v[204:207], v[80:83]
	v_mfma_f32_16x16x32_bf16 v[68:71], v[220:223], v[212:215], v[68:71]
	v_mfma_f32_16x16x32_bf16 v[64:67], v[240:243], v[212:215], v[64:67]
	s_setprio 0
	s_mov_b32 m0, s19
	v_lshl_add_u64 v[244:245], s[8:9], 0, v[178:179]
	s_barrier
	ds_read_b128 v[148:151], v202 offset:16384
	ds_read_b128 v[152:155], v202 offset:17408
	ds_read_b128 v[156:159], v202 offset:18432
	ds_read_b128 v[160:163], v202 offset:19456
	ds_read_b128 v[164:167], v202 offset:20480
	ds_read_b128 v[204:207], v202 offset:21504
	ds_read_b128 v[208:211], v202 offset:22528
	ds_read_b128 v[212:215], v202 offset:23552
	global_load_lds_dwordx4 v[244:245], off
	v_lshl_add_u64 v[246:247], s[8:9], 0, v[174:175]
	s_mov_b32 m0, s21
	s_nop 0
	global_load_lds_dwordx4 v[246:247], off
	s_barrier
	s_waitcnt lgkmcnt(0)
	s_setprio 1
	s_waitcnt lgkmcnt(0)
	v_mfma_f32_16x16x32_bf16 v[60:63], v[132:135], v[148:151], v[60:63]
	v_mfma_f32_16x16x32_bf16 v[56:59], v[140:143], v[148:151], v[56:59]
	v_mfma_f32_16x16x32_bf16 v[44:47], v[132:135], v[156:159], v[44:47]
	v_mfma_f32_16x16x32_bf16 v[40:43], v[140:143], v[156:159], v[40:43]
	v_mfma_f32_16x16x32_bf16 v[28:31], v[132:135], v[164:167], v[28:31]
	v_mfma_f32_16x16x32_bf16 v[24:27], v[140:143], v[164:167], v[24:27]
	v_mfma_f32_16x16x32_bf16 v[12:15], v[132:135], v[208:211], v[12:15]
	v_mfma_f32_16x16x32_bf16 v[8:11], v[140:143], v[208:211], v[8:11]
	v_mfma_f32_16x16x32_bf16 v[60:63], v[136:139], v[152:155], v[60:63]
	v_mfma_f32_16x16x32_bf16 v[56:59], v[144:147], v[152:155], v[56:59]
	v_mfma_f32_16x16x32_bf16 v[44:47], v[136:139], v[160:163], v[44:47]
	v_mfma_f32_16x16x32_bf16 v[40:43], v[144:147], v[160:163], v[40:43]
	v_mfma_f32_16x16x32_bf16 v[28:31], v[136:139], v[204:207], v[28:31]
	v_mfma_f32_16x16x32_bf16 v[24:27], v[144:147], v[204:207], v[24:27]
	v_mfma_f32_16x16x32_bf16 v[12:15], v[136:139], v[212:215], v[12:15]
	v_mfma_f32_16x16x32_bf16 v[8:11], v[144:147], v[212:215], v[8:11]
	s_setprio 0
	s_barrier
	s_add_u32 s30, s30, s90
	s_addc_u32 s31, s31, s91
	s_add_i32 s46, s46, s53
	v_lshl_add_u64 v[248:249], s[30:31], 0, v[180:181]
	s_mov_b32 m0, s46
	v_lshl_add_u64 v[250:251], s[30:31], 0, v[176:177]
	global_load_lds_dwordx4 v[248:249], off
	s_add_i32 m0, s46, 0x2000
	s_nop 0
	global_load_lds_dwordx4 v[250:251], off
	s_waitcnt vmcnt(6)
	s_barrier
	s_setprio 1
	v_mfma_f32_16x16x32_bf16 v[52:55], v[216:219], v[148:151], v[52:55]
	v_mfma_f32_16x16x32_bf16 v[48:51], v[232:235], v[148:151], v[48:51]
	v_mfma_f32_16x16x32_bf16 v[36:39], v[216:219], v[156:159], v[36:39]
	v_mfma_f32_16x16x32_bf16 v[32:35], v[232:235], v[156:159], v[32:35]
	v_mfma_f32_16x16x32_bf16 v[20:23], v[216:219], v[164:167], v[20:23]
	v_mfma_f32_16x16x32_bf16 v[16:19], v[232:235], v[164:167], v[16:19]
	v_mfma_f32_16x16x32_bf16 v[4:7], v[216:219], v[208:211], v[4:7]
	v_mfma_f32_16x16x32_bf16 v[0:3], v[232:235], v[208:211], v[0:3]
	v_mfma_f32_16x16x32_bf16 v[52:55], v[220:223], v[152:155], v[52:55]
	v_mfma_f32_16x16x32_bf16 v[48:51], v[240:243], v[152:155], v[48:51]
	v_mfma_f32_16x16x32_bf16 v[36:39], v[220:223], v[160:163], v[36:39]
	v_mfma_f32_16x16x32_bf16 v[32:35], v[240:243], v[160:163], v[32:35]
	v_mfma_f32_16x16x32_bf16 v[20:23], v[220:223], v[204:207], v[20:23]
	v_mfma_f32_16x16x32_bf16 v[16:19], v[240:243], v[204:207], v[16:19]
	v_mfma_f32_16x16x32_bf16 v[4:7], v[220:223], v[212:215], v[4:7]
	v_mfma_f32_16x16x32_bf16 v[0:3], v[240:243], v[212:215], v[0:3]
	s_setprio 0
	v_add_u32_e32 v144, s77, v193
	s_barrier
	ds_read_b128 v[132:135], v144
	ds_read_b128 v[136:139], v144 offset:1024
	ds_read_b128 v[140:143], v144 offset:2048
	ds_read_b128 v[144:147], v144 offset:3072
	s_add_u32 s8, s8, s22
	s_addc_u32 s9, s9, s23
	s_mov_b32 m0, s64
	v_lshl_add_u64 v[216:217], s[8:9], 0, v[178:179]
	ds_read_b128 v[148:151], v202 offset:32768
	ds_read_b128 v[152:155], v202 offset:33792
	ds_read_b128 v[156:159], v202 offset:34816
	ds_read_b128 v[160:163], v202 offset:35840
	ds_read_b128 v[164:167], v202 offset:36864
	ds_read_b128 v[204:207], v202 offset:37888
	ds_read_b128 v[208:211], v202 offset:38912
	ds_read_b128 v[212:215], v202 offset:39936
	global_load_lds_dwordx4 v[216:217], off
	v_lshl_add_u64 v[216:217], s[8:9], 0, v[174:175]
	s_mov_b32 m0, s65
	s_nop 0
	global_load_lds_dwordx4 v[216:217], off
	s_waitcnt lgkmcnt(8)
	s_barrier
	s_waitcnt lgkmcnt(0)
	s_setprio 1
	s_waitcnt lgkmcnt(0)
	v_mfma_f32_16x16x32_bf16 v[124:127], v[132:135], v[148:151], v[124:127]
	v_mfma_f32_16x16x32_bf16 v[120:123], v[140:143], v[148:151], v[120:123]
	v_mfma_f32_16x16x32_bf16 v[108:111], v[132:135], v[156:159], v[108:111]
	v_mfma_f32_16x16x32_bf16 v[104:107], v[140:143], v[156:159], v[104:107]
	v_mfma_f32_16x16x32_bf16 v[92:95], v[132:135], v[164:167], v[92:95]
	v_mfma_f32_16x16x32_bf16 v[88:91], v[140:143], v[164:167], v[88:91]
	v_mfma_f32_16x16x32_bf16 v[76:79], v[132:135], v[208:211], v[76:79]
	v_mfma_f32_16x16x32_bf16 v[72:75], v[140:143], v[208:211], v[72:75]
	v_mfma_f32_16x16x32_bf16 v[124:127], v[136:139], v[152:155], v[124:127]
	v_mfma_f32_16x16x32_bf16 v[120:123], v[144:147], v[152:155], v[120:123]
	v_mfma_f32_16x16x32_bf16 v[108:111], v[136:139], v[160:163], v[108:111]
	v_mfma_f32_16x16x32_bf16 v[104:107], v[144:147], v[160:163], v[104:107]
	v_mfma_f32_16x16x32_bf16 v[92:95], v[136:139], v[204:207], v[92:95]
	v_mfma_f32_16x16x32_bf16 v[88:91], v[144:147], v[204:207], v[88:91]
	v_mfma_f32_16x16x32_bf16 v[76:79], v[136:139], v[212:215], v[76:79]
	v_mfma_f32_16x16x32_bf16 v[72:75], v[144:147], v[212:215], v[72:75]
	s_setprio 0
	s_barrier
	s_add_i32 s8, 0, 0x1c000
	s_add_i32 s9, s77, s53
	v_add_u32_e32 v203, s8, v193
	v_lshl_add_u64 v[190:191], v[190:191], 0, s[58:59]
	s_mov_b32 m0, s9
	ds_read_b128 v[216:219], v203
	ds_read_b128 v[220:223], v203 offset:1024
	ds_read_b128 v[232:235], v203 offset:2048
	ds_read_b128 v[240:243], v203 offset:3072
	global_load_lds_dwordx4 v[190:191], off
	v_lshl_add_u64 v[190:191], v[224:225], 0, s[58:59]
	s_add_i32 m0, s9, 0x2000
	s_nop 0
	global_load_lds_dwordx4 v[190:191], off
	s_barrier
	s_waitcnt lgkmcnt(0)
	s_setprio 1
	s_waitcnt lgkmcnt(0)
	v_mfma_f32_16x16x32_bf16 v[116:119], v[216:219], v[148:151], v[116:119]
	v_mfma_f32_16x16x32_bf16 v[112:115], v[232:235], v[148:151], v[112:115]
	v_mfma_f32_16x16x32_bf16 v[100:103], v[216:219], v[156:159], v[100:103]
	v_mfma_f32_16x16x32_bf16 v[96:99], v[232:235], v[156:159], v[96:99]
	v_mfma_f32_16x16x32_bf16 v[84:87], v[216:219], v[164:167], v[84:87]
	v_mfma_f32_16x16x32_bf16 v[80:83], v[232:235], v[164:167], v[80:83]
	v_mfma_f32_16x16x32_bf16 v[68:71], v[216:219], v[208:211], v[68:71]
	v_mfma_f32_16x16x32_bf16 v[64:67], v[232:235], v[208:211], v[64:67]
	v_mfma_f32_16x16x32_bf16 v[116:119], v[220:223], v[152:155], v[116:119]
	v_mfma_f32_16x16x32_bf16 v[112:115], v[240:243], v[152:155], v[112:115]
	v_mfma_f32_16x16x32_bf16 v[100:103], v[220:223], v[160:163], v[100:103]
	v_mfma_f32_16x16x32_bf16 v[96:99], v[240:243], v[160:163], v[96:99]
	v_mfma_f32_16x16x32_bf16 v[84:87], v[220:223], v[204:207], v[84:87]
	v_mfma_f32_16x16x32_bf16 v[80:83], v[240:243], v[204:207], v[80:83]
	v_mfma_f32_16x16x32_bf16 v[68:71], v[220:223], v[212:215], v[68:71]
	v_mfma_f32_16x16x32_bf16 v[64:67], v[240:243], v[212:215], v[64:67]
	s_setprio 0
	s_mov_b32 m0, s66
	v_lshl_add_u64 v[190:191], v[244:245], 0, s[58:59]
	s_barrier
	ds_read_b128 v[148:151], v202 offset:49152
	ds_read_b128 v[152:155], v202 offset:50176
	ds_read_b128 v[156:159], v202 offset:51200
	ds_read_b128 v[160:163], v202 offset:52224
	ds_read_b128 v[164:167], v202 offset:53248
	ds_read_b128 v[204:207], v202 offset:54272
	ds_read_b128 v[208:211], v202 offset:55296
	ds_read_b128 v[212:215], v202 offset:56320
	global_load_lds_dwordx4 v[190:191], off
	v_lshl_add_u64 v[190:191], v[246:247], 0, s[58:59]
	s_mov_b32 m0, s67
	s_nop 0
	global_load_lds_dwordx4 v[190:191], off
	s_barrier
	s_waitcnt lgkmcnt(0)
	s_setprio 1
	s_waitcnt lgkmcnt(0)
	v_mfma_f32_16x16x32_bf16 v[60:63], v[132:135], v[148:151], v[60:63]
	v_mfma_f32_16x16x32_bf16 v[56:59], v[140:143], v[148:151], v[56:59]
	v_mfma_f32_16x16x32_bf16 v[44:47], v[132:135], v[156:159], v[44:47]
	v_mfma_f32_16x16x32_bf16 v[40:43], v[140:143], v[156:159], v[40:43]
	v_mfma_f32_16x16x32_bf16 v[28:31], v[132:135], v[164:167], v[28:31]
	v_mfma_f32_16x16x32_bf16 v[24:27], v[140:143], v[164:167], v[24:27]
	v_mfma_f32_16x16x32_bf16 v[12:15], v[132:135], v[208:211], v[12:15]
	v_mfma_f32_16x16x32_bf16 v[8:11], v[140:143], v[208:211], v[8:11]
	v_mfma_f32_16x16x32_bf16 v[60:63], v[136:139], v[152:155], v[60:63]
	v_mfma_f32_16x16x32_bf16 v[56:59], v[144:147], v[152:155], v[56:59]
	v_mfma_f32_16x16x32_bf16 v[44:47], v[136:139], v[160:163], v[44:47]
	v_mfma_f32_16x16x32_bf16 v[40:43], v[144:147], v[160:163], v[40:43]
	v_mfma_f32_16x16x32_bf16 v[28:31], v[136:139], v[204:207], v[28:31]
	v_mfma_f32_16x16x32_bf16 v[24:27], v[144:147], v[204:207], v[24:27]
	v_mfma_f32_16x16x32_bf16 v[12:15], v[136:139], v[212:215], v[12:15]
	v_mfma_f32_16x16x32_bf16 v[8:11], v[144:147], v[212:215], v[8:11]
	s_setprio 0
	s_barrier
	s_add_i32 s8, s8, s53
	v_lshl_add_u64 v[132:133], v[248:249], 0, s[58:59]
	s_mov_b32 m0, s8
	s_nop 0
	global_load_lds_dwordx4 v[132:133], off
	v_lshl_add_u64 v[132:133], v[250:251], 0, s[58:59]
	s_add_i32 m0, s8, 0x2000
	s_nop 0
	global_load_lds_dwordx4 v[132:133], off
	s_waitcnt vmcnt(6)
	s_barrier
	s_setprio 1
	v_mfma_f32_16x16x32_bf16 v[52:55], v[216:219], v[148:151], v[52:55]
	v_mfma_f32_16x16x32_bf16 v[48:51], v[232:235], v[148:151], v[48:51]
	v_mfma_f32_16x16x32_bf16 v[36:39], v[216:219], v[156:159], v[36:39]
	v_mfma_f32_16x16x32_bf16 v[32:35], v[232:235], v[156:159], v[32:35]
	v_mfma_f32_16x16x32_bf16 v[20:23], v[216:219], v[164:167], v[20:23]
	v_mfma_f32_16x16x32_bf16 v[16:19], v[232:235], v[164:167], v[16:19]
	v_mfma_f32_16x16x32_bf16 v[4:7], v[216:219], v[208:211], v[4:7]
	v_mfma_f32_16x16x32_bf16 v[0:3], v[232:235], v[208:211], v[0:3]
	v_mfma_f32_16x16x32_bf16 v[52:55], v[220:223], v[152:155], v[52:55]
	v_mfma_f32_16x16x32_bf16 v[48:51], v[240:243], v[152:155], v[48:51]
	v_mfma_f32_16x16x32_bf16 v[36:39], v[220:223], v[160:163], v[36:39]
	v_mfma_f32_16x16x32_bf16 v[32:35], v[240:243], v[160:163], v[32:35]
	v_mfma_f32_16x16x32_bf16 v[20:23], v[220:223], v[204:207], v[20:23]
	v_mfma_f32_16x16x32_bf16 v[16:19], v[240:243], v[204:207], v[16:19]
	v_mfma_f32_16x16x32_bf16 v[4:7], v[220:223], v[212:215], v[4:7]
	v_mfma_f32_16x16x32_bf16 v[0:3], v[240:243], v[212:215], v[0:3]
	s_setprio 0
	s_add_u32 s4, s4, 0x100
	s_addc_u32 s5, s5, 0
	s_mov_b32 s46, s38
	s_add_u32 s8, s26, s4
	s_addc_u32 s9, s27, s5
	s_add_u32 s8, s8, 0x100
	s_addc_u32 s9, s9, 0
	s_add_u32 s30, s44, s4
	s_addc_u32 s31, s45, s5
	s_cmp_eq_u32 s71, s46
	s_cselect_b32 s9, s13, s9
	s_cselect_b32 s8, s12, s8
	s_cselect_b32 s31, s57, s31
	s_cselect_b32 s30, s56, s30
	s_add_i32 s38, s46, 2
	s_cmp_lt_i32 s46, s68
	s_cselect_b32 s47, 1, 0
	s_andn2_b32 s47, s47, s96
	s_cmp_lg_u32 s47, 0
	s_mov_b32 s47, 0x10000
	s_barrier
	s_cbranch_scc1 .Lkl_fast
	s_cmp_ge_i32 s46, s68
	s_cbranch_scc0 .LBB0_754
	s_load_dwordx2 s[26:27], s[0:1], 0x150
	s_mov_b64 s[4:5], -1
	s_mov_b64 s[8:9], 0
	s_cmp_lt_i32 s50, 5
	s_mov_b64 s[44:45], 0
	s_cbranch_scc1 .LBB0_785
	s_cmp_gt_i32 s50, 7
	s_cbranch_scc0 .LBB0_775
	s_cmp_gt_i32 s50, 8
	s_cbranch_scc0 .LBB0_772
	s_cmp_gt_i32 s50, 10
	s_cbranch_scc0 .LBB0_768
	s_cmp_eq_u32 s50, 11
	s_mov_b64 s[44:45], -1
	s_cbranch_scc0 .LBB0_767
	s_waitcnt lgkmcnt(0)
	s_add_u32 s4, s26, 0x9640000
	s_addc_u32 s5, s27, 0
	s_lshl_b32 s38, s70, 1
	s_add_u32 s30, s26, s38
	s_addc_u32 s31, s27, 0
	v_lshlrev_b32_e32 v128, 1, v172
	v_mov_b32_e32 v129, v169
	v_lshl_add_u64 v[130:131], s[30:31], 0, v[128:129]
	s_lshl_b64 s[30:31], s[24:25], 1
	v_add_u32_e32 v132, s54, v192
	v_lshl_add_u64 v[130:131], v[130:131], 0, s[30:31]
	s_mov_b64 s[44:45], 0x1a642000
	v_lshl_add_u64 v[130:131], v[130:131], 0, s[44:45]
	v_or_b32_e32 v133, 16, v132
	v_mad_i64_i32 v[142:143], s[44:45], v133, s37, v[130:131]
	v_or_b32_e32 v133, 32, v132
	v_mad_i64_i32 v[150:151], s[44:45], v133, s37, v[130:131]
	v_or_b32_e32 v133, 48, v132
	v_mad_i64_i32 v[134:135], s[44:45], v132, s37, v[130:131]
	v_mad_i64_i32 v[158:159], s[44:45], v133, s37, v[130:131]
	global_load_dwordx2 v[136:137], v[134:135], off
	global_load_dwordx2 v[138:139], v[134:135], off offset:32
	global_load_dwordx2 v[140:141], v[134:135], off offset:256
	s_nop 0
	global_load_dwordx2 v[134:135], v[134:135], off offset:288
	s_nop 0
	global_load_dwordx2 v[144:145], v[142:143], off
	global_load_dwordx2 v[146:147], v[142:143], off offset:32
	global_load_dwordx2 v[148:149], v[142:143], off offset:256
	s_nop 0
	global_load_dwordx2 v[142:143], v[142:143], off offset:288
	s_nop 0
	global_load_dwordx2 v[152:153], v[150:151], off
	global_load_dwordx2 v[154:155], v[150:151], off offset:32
	global_load_dwordx2 v[156:157], v[150:151], off offset:256
	s_nop 0
	global_load_dwordx2 v[150:151], v[150:151], off offset:288
	s_nop 0
	global_load_dwordx2 v[160:161], v[158:159], off
	global_load_dwordx2 v[162:163], v[158:159], off offset:32
	global_load_dwordx2 v[164:165], v[158:159], off offset:256
	s_nop 0
	global_load_dwordx2 v[158:159], v[158:159], off offset:288
	v_ashrrev_i32_e32 v133, 31, v132
	s_waitcnt vmcnt(0)
	v_lshlrev_b32_e32 v166, 16, v136
	v_and_b32_e32 v136, 0xffff0000, v136
	v_lshlrev_b64 v[132:133], 12, v[132:133]
	v_mul_f32_e32 v166, v124, v166
	v_mul_f32_e32 v136, v125, v136
	v_lshl_add_u64 v[132:133], s[4:5], 0, v[132:133]
	v_cvt_pk_bf16_f32 v136, v166, v136
	v_lshlrev_b32_e32 v166, 16, v137
	v_and_b32_e32 v137, 0xffff0000, v137
	v_lshl_add_u64 v[132:133], v[132:133], 0, s[30:31]
	v_mul_f32_e32 v137, v127, v137
	v_lshl_add_u64 v[132:133], v[132:133], 0, s[38:39]
	v_mul_f32_e32 v166, v126, v166
	v_cvt_pk_bf16_f32 v137, v166, v137
	v_lshl_add_u64 v[132:133], v[132:133], 0, v[128:129]
	global_store_dwordx2 v[132:133], v[136:137], off
	v_lshlrev_b32_e32 v136, 16, v138
	v_and_b32_e32 v137, 0xffff0000, v138
	v_mul_f32_e32 v136, v120, v136
	v_mul_f32_e32 v137, v121, v137
	v_cvt_pk_bf16_f32 v136, v136, v137
	v_lshlrev_b32_e32 v137, 16, v139
	v_mul_f32_e32 v137, v122, v137
	v_and_b32_e32 v138, 0xffff0000, v139
	v_mul_f32_e32 v138, v123, v138
	v_cvt_pk_bf16_f32 v137, v137, v138
	global_store_dwordx2 v[132:133], v[136:137], off offset:32
	v_lshlrev_b32_e32 v136, 16, v140
	v_and_b32_e32 v137, 0xffff0000, v140
	v_mul_f32_e32 v136, v116, v136
	v_mul_f32_e32 v137, v117, v137
	v_cvt_pk_bf16_f32 v136, v136, v137
	v_lshlrev_b32_e32 v137, 16, v141
	v_mul_f32_e32 v137, v118, v137
	v_and_b32_e32 v138, 0xffff0000, v141
	v_mul_f32_e32 v138, v119, v138
	v_cvt_pk_bf16_f32 v137, v137, v138
	global_store_dwordx2 v[132:133], v[136:137], off offset:256
	v_lshlrev_b32_e32 v136, 16, v134
	v_and_b32_e32 v134, 0xffff0000, v134
	v_mul_f32_e32 v136, v112, v136
	v_mul_f32_e32 v134, v113, v134
	v_cvt_pk_bf16_f32 v134, v136, v134
	v_lshlrev_b32_e32 v136, 16, v135
	v_and_b32_e32 v135, 0xffff0000, v135
	v_mul_f32_e32 v135, v115, v135
	v_mul_f32_e32 v136, v114, v136
	v_cvt_pk_bf16_f32 v135, v136, v135
	global_store_dwordx2 v[132:133], v[134:135], off offset:288
	v_lshlrev_b32_e32 v132, 16, v144
	v_and_b32_e32 v133, 0xffff0000, v144
	v_mul_f32_e32 v132, v108, v132
	v_mul_f32_e32 v133, v109, v133
	v_cvt_pk_bf16_f32 v132, v132, v133
	v_lshlrev_b32_e32 v133, 16, v145
	v_and_b32_e32 v134, 0xffff0000, v145
	v_mul_f32_e32 v133, v110, v133
	v_mul_f32_e32 v134, v111, v134
	v_cvt_pk_bf16_f32 v133, v133, v134
	v_add_u32_e32 v134, s54, v194
	v_ashrrev_i32_e32 v135, 31, v134
	v_lshlrev_b64 v[134:135], 12, v[134:135]
	v_lshl_add_u64 v[134:135], s[4:5], 0, v[134:135]
	v_lshl_add_u64 v[134:135], v[134:135], 0, s[30:31]
	v_lshl_add_u64 v[134:135], v[134:135], 0, s[38:39]
	v_lshl_add_u64 v[134:135], v[134:135], 0, v[128:129]
	global_store_dwordx2 v[134:135], v[132:133], off
	v_lshlrev_b32_e32 v132, 16, v146
	v_and_b32_e32 v133, 0xffff0000, v146
	v_mul_f32_e32 v132, v104, v132
	v_mul_f32_e32 v133, v105, v133
	v_cvt_pk_bf16_f32 v132, v132, v133
	v_lshlrev_b32_e32 v133, 16, v147
	v_mul_f32_e32 v133, v106, v133
	v_and_b32_e32 v136, 0xffff0000, v147
	v_mul_f32_e32 v136, v107, v136
	v_cvt_pk_bf16_f32 v133, v133, v136
	global_store_dwordx2 v[134:135], v[132:133], off offset:32
	v_lshlrev_b32_e32 v132, 16, v148
	v_and_b32_e32 v133, 0xffff0000, v148
	v_mul_f32_e32 v132, v100, v132
	v_mul_f32_e32 v133, v101, v133
	v_cvt_pk_bf16_f32 v132, v132, v133
	v_lshlrev_b32_e32 v133, 16, v149
	v_mul_f32_e32 v133, v102, v133
	v_and_b32_e32 v136, 0xffff0000, v149
	v_mul_f32_e32 v136, v103, v136
	v_cvt_pk_bf16_f32 v133, v133, v136
	global_store_dwordx2 v[134:135], v[132:133], off offset:256
	v_lshlrev_b32_e32 v132, 16, v142
	v_and_b32_e32 v133, 0xffff0000, v142
	v_mul_f32_e32 v132, v96, v132
	v_mul_f32_e32 v133, v97, v133
	v_cvt_pk_bf16_f32 v132, v132, v133
	v_lshlrev_b32_e32 v133, 16, v143
	v_mul_f32_e32 v133, v98, v133
	v_and_b32_e32 v136, 0xffff0000, v143
	v_mul_f32_e32 v136, v99, v136
	v_cvt_pk_bf16_f32 v133, v133, v136
	global_store_dwordx2 v[134:135], v[132:133], off offset:288
	v_lshlrev_b32_e32 v132, 16, v152
	v_and_b32_e32 v133, 0xffff0000, v152
	v_mul_f32_e32 v132, v92, v132
	v_mul_f32_e32 v133, v93, v133
	v_cvt_pk_bf16_f32 v132, v132, v133
	v_lshlrev_b32_e32 v133, 16, v153
	v_and_b32_e32 v134, 0xffff0000, v153
	v_mul_f32_e32 v133, v94, v133
	v_mul_f32_e32 v134, v95, v134
	v_cvt_pk_bf16_f32 v133, v133, v134
	v_add_u32_e32 v134, s54, v195
	v_ashrrev_i32_e32 v135, 31, v134
	v_lshlrev_b64 v[134:135], 12, v[134:135]
	v_lshl_add_u64 v[134:135], s[4:5], 0, v[134:135]
	v_lshl_add_u64 v[134:135], v[134:135], 0, s[30:31]
	v_lshl_add_u64 v[134:135], v[134:135], 0, s[38:39]
	v_lshl_add_u64 v[134:135], v[134:135], 0, v[128:129]
	global_store_dwordx2 v[134:135], v[132:133], off
	v_lshlrev_b32_e32 v132, 16, v154
	v_and_b32_e32 v133, 0xffff0000, v154
	v_mul_f32_e32 v132, v88, v132
	v_mul_f32_e32 v133, v89, v133
	v_cvt_pk_bf16_f32 v132, v132, v133
	v_lshlrev_b32_e32 v133, 16, v155
	v_mul_f32_e32 v133, v90, v133
	v_and_b32_e32 v136, 0xffff0000, v155
	v_mul_f32_e32 v136, v91, v136
	v_cvt_pk_bf16_f32 v133, v133, v136
	global_store_dwordx2 v[134:135], v[132:133], off offset:32
	v_lshlrev_b32_e32 v132, 16, v156
	v_and_b32_e32 v133, 0xffff0000, v156
	v_mul_f32_e32 v132, v84, v132
	v_mul_f32_e32 v133, v85, v133
	v_cvt_pk_bf16_f32 v132, v132, v133
	v_lshlrev_b32_e32 v133, 16, v157
	v_mul_f32_e32 v133, v86, v133
	v_and_b32_e32 v136, 0xffff0000, v157
	v_mul_f32_e32 v136, v87, v136
	v_cvt_pk_bf16_f32 v133, v133, v136
	global_store_dwordx2 v[134:135], v[132:133], off offset:256
	v_lshlrev_b32_e32 v132, 16, v150
	v_and_b32_e32 v133, 0xffff0000, v150
	v_mul_f32_e32 v132, v80, v132
	v_mul_f32_e32 v133, v81, v133
	v_cvt_pk_bf16_f32 v132, v132, v133
	v_lshlrev_b32_e32 v133, 16, v151
	v_mul_f32_e32 v133, v82, v133
	v_and_b32_e32 v136, 0xffff0000, v151
	v_mul_f32_e32 v136, v83, v136
	v_cvt_pk_bf16_f32 v133, v133, v136
	global_store_dwordx2 v[134:135], v[132:133], off offset:288
	v_lshlrev_b32_e32 v132, 16, v160
	v_and_b32_e32 v133, 0xffff0000, v160
	v_mul_f32_e32 v132, v76, v132
	v_mul_f32_e32 v133, v77, v133
	v_cvt_pk_bf16_f32 v132, v132, v133
	v_lshlrev_b32_e32 v133, 16, v161
	v_and_b32_e32 v134, 0xffff0000, v161
	v_mul_f32_e32 v133, v78, v133
	v_mul_f32_e32 v134, v79, v134
	v_cvt_pk_bf16_f32 v133, v133, v134
	v_add_u32_e32 v134, s54, v196
	v_ashrrev_i32_e32 v135, 31, v134
	v_lshlrev_b64 v[134:135], 12, v[134:135]
	v_lshl_add_u64 v[134:135], s[4:5], 0, v[134:135]
	v_lshl_add_u64 v[134:135], v[134:135], 0, s[30:31]
	v_lshl_add_u64 v[134:135], v[134:135], 0, s[38:39]
	v_lshl_add_u64 v[134:135], v[134:135], 0, v[128:129]
	global_store_dwordx2 v[134:135], v[132:133], off
	v_lshlrev_b32_e32 v132, 16, v162
	v_and_b32_e32 v133, 0xffff0000, v162
	v_mul_f32_e32 v132, v72, v132
	v_mul_f32_e32 v133, v73, v133
	v_cvt_pk_bf16_f32 v132, v132, v133
	v_lshlrev_b32_e32 v133, 16, v163
	v_mul_f32_e32 v133, v74, v133
	v_and_b32_e32 v136, 0xffff0000, v163
	v_mul_f32_e32 v136, v75, v136
	v_cvt_pk_bf16_f32 v133, v133, v136
	global_store_dwordx2 v[134:135], v[132:133], off offset:32
	v_lshlrev_b32_e32 v132, 16, v164
	v_and_b32_e32 v133, 0xffff0000, v164
	v_mul_f32_e32 v132, v68, v132
	v_mul_f32_e32 v133, v69, v133
	v_cvt_pk_bf16_f32 v132, v132, v133
	v_lshlrev_b32_e32 v133, 16, v165
	v_mul_f32_e32 v133, v70, v133
	v_and_b32_e32 v136, 0xffff0000, v165
	v_mul_f32_e32 v136, v71, v136
	v_cvt_pk_bf16_f32 v133, v133, v136
	global_store_dwordx2 v[134:135], v[132:133], off offset:256
	v_lshlrev_b32_e32 v132, 16, v158
	v_and_b32_e32 v133, 0xffff0000, v158
	v_mul_f32_e32 v132, v64, v132
	v_mul_f32_e32 v133, v65, v133
	v_cvt_pk_bf16_f32 v132, v132, v133
	v_lshlrev_b32_e32 v133, 16, v159
	v_mul_f32_e32 v133, v66, v133
	v_and_b32_e32 v136, 0xffff0000, v159
	v_mul_f32_e32 v136, v67, v136
	v_cvt_pk_bf16_f32 v133, v133, v136
	global_store_dwordx2 v[134:135], v[132:133], off offset:288
	v_add_u32_e32 v132, s54, v197
	v_or_b32_e32 v133, 16, v132
	v_mad_i64_i32 v[142:143], s[44:45], v133, s37, v[130:131]
	v_or_b32_e32 v133, 32, v132
	v_mad_i64_i32 v[150:151], s[44:45], v133, s37, v[130:131]
	v_or_b32_e32 v133, 48, v132
	v_mad_i64_i32 v[134:135], s[44:45], v132, s37, v[130:131]
	v_mad_i64_i32 v[130:131], s[44:45], v133, s37, v[130:131]
	global_load_dwordx2 v[136:137], v[134:135], off
	global_load_dwordx2 v[138:139], v[134:135], off offset:32
	global_load_dwordx2 v[140:141], v[134:135], off offset:256
	s_nop 0
	global_load_dwordx2 v[134:135], v[134:135], off offset:288
	s_nop 0
	global_load_dwordx2 v[144:145], v[142:143], off
	global_load_dwordx2 v[146:147], v[142:143], off offset:32
	global_load_dwordx2 v[148:149], v[142:143], off offset:256
	s_nop 0
	global_load_dwordx2 v[142:143], v[142:143], off offset:288
	s_nop 0
	global_load_dwordx2 v[152:153], v[150:151], off
	global_load_dwordx2 v[154:155], v[150:151], off offset:32
	global_load_dwordx2 v[156:157], v[150:151], off offset:256
	s_nop 0
	global_load_dwordx2 v[150:151], v[150:151], off offset:288
	s_nop 0
	global_load_dwordx2 v[158:159], v[130:131], off
	global_load_dwordx2 v[160:161], v[130:131], off offset:32
	global_load_dwordx2 v[162:163], v[130:131], off offset:256
	s_nop 0
	global_load_dwordx2 v[130:131], v[130:131], off offset:288
	v_ashrrev_i32_e32 v133, 31, v132
	s_waitcnt vmcnt(15)
	v_lshlrev_b32_e32 v164, 16, v136
	v_and_b32_e32 v136, 0xffff0000, v136
	v_lshlrev_b64 v[132:133], 12, v[132:133]
	v_mul_f32_e32 v164, v60, v164
	v_mul_f32_e32 v136, v61, v136
	v_lshl_add_u64 v[132:133], s[4:5], 0, v[132:133]
	v_cvt_pk_bf16_f32 v136, v164, v136
	v_lshlrev_b32_e32 v164, 16, v137
	v_and_b32_e32 v137, 0xffff0000, v137
	v_lshl_add_u64 v[132:133], v[132:133], 0, s[30:31]
	v_mul_f32_e32 v137, v63, v137
	v_lshl_add_u64 v[132:133], v[132:133], 0, s[38:39]
	v_mul_f32_e32 v164, v62, v164
	v_cvt_pk_bf16_f32 v137, v164, v137
	v_lshl_add_u64 v[132:133], v[132:133], 0, v[128:129]
	global_store_dwordx2 v[132:133], v[136:137], off
	s_waitcnt vmcnt(15)
	v_lshlrev_b32_e32 v136, 16, v138
	v_and_b32_e32 v137, 0xffff0000, v138
	v_mul_f32_e32 v136, v56, v136
	v_mul_f32_e32 v137, v57, v137
	v_cvt_pk_bf16_f32 v136, v136, v137
	v_lshlrev_b32_e32 v137, 16, v139
	v_mul_f32_e32 v137, v58, v137
	v_and_b32_e32 v138, 0xffff0000, v139
	v_mul_f32_e32 v138, v59, v138
	v_cvt_pk_bf16_f32 v137, v137, v138
	global_store_dwordx2 v[132:133], v[136:137], off offset:32
	s_waitcnt vmcnt(15)
	v_lshlrev_b32_e32 v136, 16, v140
	v_and_b32_e32 v137, 0xffff0000, v140
	v_mul_f32_e32 v136, v52, v136
	v_mul_f32_e32 v137, v53, v137
	v_cvt_pk_bf16_f32 v136, v136, v137
	v_lshlrev_b32_e32 v137, 16, v141
	v_mul_f32_e32 v137, v54, v137
	v_and_b32_e32 v138, 0xffff0000, v141
	v_mul_f32_e32 v138, v55, v138
	v_cvt_pk_bf16_f32 v137, v137, v138
	global_store_dwordx2 v[132:133], v[136:137], off offset:256
	s_waitcnt vmcnt(15)
	v_lshlrev_b32_e32 v136, 16, v134
	v_and_b32_e32 v134, 0xffff0000, v134
	v_mul_f32_e32 v136, v48, v136
	v_mul_f32_e32 v134, v49, v134
	v_cvt_pk_bf16_f32 v134, v136, v134
	v_lshlrev_b32_e32 v136, 16, v135
	v_and_b32_e32 v135, 0xffff0000, v135
	v_mul_f32_e32 v135, v51, v135
	v_mul_f32_e32 v136, v50, v136
	v_cvt_pk_bf16_f32 v135, v136, v135
	global_store_dwordx2 v[132:133], v[134:135], off offset:288
	s_waitcnt vmcnt(15)
	v_lshlrev_b32_e32 v132, 16, v144
	v_and_b32_e32 v133, 0xffff0000, v144
	v_mul_f32_e32 v132, v44, v132
	v_mul_f32_e32 v133, v45, v133
	v_cvt_pk_bf16_f32 v132, v132, v133
	v_lshlrev_b32_e32 v133, 16, v145
	v_and_b32_e32 v134, 0xffff0000, v145
	v_mul_f32_e32 v133, v46, v133
	v_mul_f32_e32 v134, v47, v134
	v_cvt_pk_bf16_f32 v133, v133, v134
	v_add_u32_e32 v134, s54, v198
	v_ashrrev_i32_e32 v135, 31, v134
	v_lshlrev_b64 v[134:135], 12, v[134:135]
	v_lshl_add_u64 v[134:135], s[4:5], 0, v[134:135]
	v_lshl_add_u64 v[134:135], v[134:135], 0, s[30:31]
	v_lshl_add_u64 v[134:135], v[134:135], 0, s[38:39]
	v_lshl_add_u64 v[134:135], v[134:135], 0, v[128:129]
	global_store_dwordx2 v[134:135], v[132:133], off
	s_waitcnt vmcnt(15)
	v_lshlrev_b32_e32 v132, 16, v146
	v_and_b32_e32 v133, 0xffff0000, v146
	v_mul_f32_e32 v132, v40, v132
	v_mul_f32_e32 v133, v41, v133
	v_cvt_pk_bf16_f32 v132, v132, v133
	v_lshlrev_b32_e32 v133, 16, v147
	v_mul_f32_e32 v133, v42, v133
	v_and_b32_e32 v136, 0xffff0000, v147
	v_mul_f32_e32 v136, v43, v136
	v_cvt_pk_bf16_f32 v133, v133, v136
	global_store_dwordx2 v[134:135], v[132:133], off offset:32
	s_waitcnt vmcnt(15)
	v_lshlrev_b32_e32 v132, 16, v148
	v_and_b32_e32 v133, 0xffff0000, v148
	v_mul_f32_e32 v132, v36, v132
	v_mul_f32_e32 v133, v37, v133
	v_cvt_pk_bf16_f32 v132, v132, v133
	v_lshlrev_b32_e32 v133, 16, v149
	v_mul_f32_e32 v133, v38, v133
	v_and_b32_e32 v136, 0xffff0000, v149
	v_mul_f32_e32 v136, v39, v136
	v_cvt_pk_bf16_f32 v133, v133, v136
	global_store_dwordx2 v[134:135], v[132:133], off offset:256
	s_waitcnt vmcnt(15)
	v_lshlrev_b32_e32 v132, 16, v142
	v_and_b32_e32 v133, 0xffff0000, v142
	v_mul_f32_e32 v132, v32, v132
	v_mul_f32_e32 v133, v33, v133
	v_cvt_pk_bf16_f32 v132, v132, v133
	v_lshlrev_b32_e32 v133, 16, v143
	v_mul_f32_e32 v133, v34, v133
	v_and_b32_e32 v136, 0xffff0000, v143
	v_mul_f32_e32 v136, v35, v136
	v_cvt_pk_bf16_f32 v133, v133, v136
	global_store_dwordx2 v[134:135], v[132:133], off offset:288
	s_waitcnt vmcnt(15)
	v_lshlrev_b32_e32 v132, 16, v152
	v_and_b32_e32 v133, 0xffff0000, v152
	v_mul_f32_e32 v132, v28, v132
	v_mul_f32_e32 v133, v29, v133
	v_cvt_pk_bf16_f32 v132, v132, v133
	v_lshlrev_b32_e32 v133, 16, v153
	v_and_b32_e32 v134, 0xffff0000, v153
	v_mul_f32_e32 v133, v30, v133
	v_mul_f32_e32 v134, v31, v134
	v_cvt_pk_bf16_f32 v133, v133, v134
	v_add_u32_e32 v134, s54, v199
	v_ashrrev_i32_e32 v135, 31, v134
	v_lshlrev_b64 v[134:135], 12, v[134:135]
	v_lshl_add_u64 v[134:135], s[4:5], 0, v[134:135]
	v_lshl_add_u64 v[134:135], v[134:135], 0, s[30:31]
	v_lshl_add_u64 v[134:135], v[134:135], 0, s[38:39]
	v_lshl_add_u64 v[134:135], v[134:135], 0, v[128:129]
	global_store_dwordx2 v[134:135], v[132:133], off
	s_waitcnt vmcnt(15)
	v_lshlrev_b32_e32 v132, 16, v154
	v_and_b32_e32 v133, 0xffff0000, v154
	v_mul_f32_e32 v132, v24, v132
	v_mul_f32_e32 v133, v25, v133
	v_cvt_pk_bf16_f32 v132, v132, v133
	v_lshlrev_b32_e32 v133, 16, v155
	v_mul_f32_e32 v133, v26, v133
	v_and_b32_e32 v136, 0xffff0000, v155
	v_mul_f32_e32 v136, v27, v136
	v_cvt_pk_bf16_f32 v133, v133, v136
	global_store_dwordx2 v[134:135], v[132:133], off offset:32
	s_waitcnt vmcnt(15)
	v_lshlrev_b32_e32 v132, 16, v156
	v_and_b32_e32 v133, 0xffff0000, v156
	v_mul_f32_e32 v132, v20, v132
	v_mul_f32_e32 v133, v21, v133
	v_cvt_pk_bf16_f32 v132, v132, v133
	v_lshlrev_b32_e32 v133, 16, v157
	v_mul_f32_e32 v133, v22, v133
	v_and_b32_e32 v136, 0xffff0000, v157
	v_mul_f32_e32 v136, v23, v136
	v_cvt_pk_bf16_f32 v133, v133, v136
	global_store_dwordx2 v[134:135], v[132:133], off offset:256
	s_waitcnt vmcnt(15)
	v_lshlrev_b32_e32 v132, 16, v150
	v_and_b32_e32 v133, 0xffff0000, v150
	v_mul_f32_e32 v132, v16, v132
	v_mul_f32_e32 v133, v17, v133
	v_cvt_pk_bf16_f32 v132, v132, v133
	v_lshlrev_b32_e32 v133, 16, v151
	v_mul_f32_e32 v133, v18, v133
	v_and_b32_e32 v136, 0xffff0000, v151
	v_mul_f32_e32 v136, v19, v136
	v_cvt_pk_bf16_f32 v133, v133, v136
	global_store_dwordx2 v[134:135], v[132:133], off offset:288
	s_waitcnt vmcnt(15)
	v_lshlrev_b32_e32 v132, 16, v158
	v_and_b32_e32 v133, 0xffff0000, v158
	v_mul_f32_e32 v132, v12, v132
	v_mul_f32_e32 v133, v13, v133
	v_cvt_pk_bf16_f32 v132, v132, v133
	v_lshlrev_b32_e32 v133, 16, v159
	v_and_b32_e32 v134, 0xffff0000, v159
	v_mul_f32_e32 v133, v14, v133
	v_mul_f32_e32 v134, v15, v134
	v_cvt_pk_bf16_f32 v133, v133, v134
	v_add_u32_e32 v134, s54, v200
	v_ashrrev_i32_e32 v135, 31, v134
	v_lshlrev_b64 v[134:135], 12, v[134:135]
	v_lshl_add_u64 v[134:135], s[4:5], 0, v[134:135]
	v_lshl_add_u64 v[134:135], v[134:135], 0, s[30:31]
	v_lshl_add_u64 v[134:135], v[134:135], 0, s[38:39]
	v_lshl_add_u64 v[128:129], v[134:135], 0, v[128:129]
	global_store_dwordx2 v[128:129], v[132:133], off
	s_waitcnt vmcnt(15)
	v_lshlrev_b32_e32 v132, 16, v160
	v_and_b32_e32 v133, 0xffff0000, v160
	v_mul_f32_e32 v132, v8, v132
	v_mul_f32_e32 v133, v9, v133
	v_cvt_pk_bf16_f32 v132, v132, v133
	v_lshlrev_b32_e32 v133, 16, v161
	v_mul_f32_e32 v133, v10, v133
	v_and_b32_e32 v134, 0xffff0000, v161
	v_mul_f32_e32 v134, v11, v134
	v_cvt_pk_bf16_f32 v133, v133, v134
	global_store_dwordx2 v[128:129], v[132:133], off offset:32
	s_waitcnt vmcnt(15)
	v_lshlrev_b32_e32 v132, 16, v162
	v_and_b32_e32 v133, 0xffff0000, v162
	v_mul_f32_e32 v132, v4, v132
	v_mul_f32_e32 v133, v5, v133
	v_cvt_pk_bf16_f32 v132, v132, v133
	v_lshlrev_b32_e32 v133, 16, v163
	v_mul_f32_e32 v133, v6, v133
	v_and_b32_e32 v134, 0xffff0000, v163
	v_mul_f32_e32 v134, v7, v134
	v_cvt_pk_bf16_f32 v133, v133, v134
	global_store_dwordx2 v[128:129], v[132:133], off offset:256
	s_waitcnt vmcnt(15)
	v_lshlrev_b32_e32 v132, 16, v130
	v_and_b32_e32 v130, 0xffff0000, v130
	v_mul_f32_e32 v132, v0, v132
	v_mul_f32_e32 v130, v1, v130
	v_cvt_pk_bf16_f32 v130, v132, v130
	v_lshlrev_b32_e32 v132, 16, v131
	v_and_b32_e32 v131, 0xffff0000, v131
	v_mul_f32_e32 v131, v3, v131
	v_mul_f32_e32 v132, v2, v132
	v_cvt_pk_bf16_f32 v131, v132, v131
	global_store_dwordx2 v[128:129], v[130:131], off offset:288
	s_mov_b64 s[44:45], 0
